# hgrn_local state update: four k-blocks of X/D LDS reads in flight instead of two (v240-255 added)
# baseline (speedup 1.0000x reference)
; #define LAS __attribute__((address_space(3)))
; #define MFMA16(a, b, c) __builtin_amdgcn_mfma_f32_16x16x32_bf16((a), (b), (c), 0, 0, 0)
; __device__ __forceinline__ void hgrn_local_ws2(Frame& F, int item) {
;     ...
;             const LAS unsigned char* bb = F.lds + (ch & 1) * HB_BYTES;
;             const LAS bf16* QD = (const LAS bf16*)(bb + HB_QD); const LAS bf16* KH = (const LAS bf16*)(bb + HB_KH); const LAS bf16* KDT = (const LAS bf16*)(bb + HB_KDT);
;             const LAS bf16* VT = (const LAS bf16*)(bb + HB_VT); const LAS float* DEC = (const LAS float*)(bb + HB_DEC);
;             f32x4 T00 = (f32x4){0.f, 0.f, 0.f, 0.f}, T01 = T00, T11 = T00;
; #pragma unroll
;             for (int kk = 0; kk < 4; ++kk) {
;                 const bf16x8 kh0 = *(const LAS bf16x8*)(KH + QDOFF(l15) + 32 * kk + 8 * quad), kh1 = *(const LAS bf16x8*)(KH + QDOFF(16 + l15) + 32 * kk + 8 * quad);
;                 const bf16x8 q0 = *(const LAS bf16x8*)(QD + QDOFF(l15) + 32 * kk + 8 * quad), q1 = *(const LAS bf16x8*)(QD + QDOFF(16 + l15) + 32 * kk + 8 * quad);
;                 T00 = MFMA16(kh0, q0, T00); T01 = MFMA16(kh0, q1, T01); T11 = MFMA16(kh1, q1, T11);
;             }
; #pragma unroll
;             for (int r = 0; r < 4; ++r) { if (4 * quad + r > l15) { T00[r] = 0.f; T11[r] = 0.f; } }
;             const bf16x8 a0 = pack8(T00, (f32x4){0.f, 0.f, 0.f, 0.f}), a1 = pack8(T01, T11);
;             f32x4 O[2][2];
; #pragma unroll
;             for (int g = 0; g < 2; ++g) { O[g][0] = (f32x4){0.f, 0.f, 0.f, 0.f}; O[g][1] = O[g][0]; }
; #pragma unroll
;             for (int kk = 0; kk < 4; ++kk) {
;                 const bf16x8 aq0 = join8(*(const LAS v2u*)(QD + QDOFF(l15) + 32 * kk + 4 * quad), *(const LAS v2u*)(QD + QDOFF(l15) + 32 * kk + 16 + 4 * quad));
;                 const bf16x8 aq1 = join8(*(const LAS v2u*)(QD + QDOFF(16 + l15) + 32 * kk + 4 * quad), *(const LAS v2u*)(QD + QDOFF(16 + l15) + 32 * kk + 16 + 4 * quad));
; #pragma unroll
;                 for (int g = 0; g < 2; ++g) { const bf16x8 bs = pack8(S[g][2 * kk], S[g][2 * kk + 1]); O[g][0] = MFMA16(aq0, bs, O[g][0]); O[g][1] = MFMA16(aq1, bs, O[g][1]); }
;             }
.LBB0_468:
	s_bitcmp1_b32 s33, 0
	s_cselect_b32 s16, 0x9ac0, 0
	s_add_i32 s92, s16, 0
	v_lshl_add_u32 v207, v176, 1, s92
	v_lshl_add_u32 v2, v175, 1, v207
	ds_read_b128 v[74:77], v2 offset:8832
	ds_read_b128 v[78:81], v2
	v_lshl_add_u32 v3, v177, 1, v207
	ds_read_b128 v[82:85], v3 offset:8832
	ds_read_b128 v[86:89], v3
	ds_read_b128 v[150:153], v2 offset:8896
	ds_read_b128 v[190:193], v2 offset:64
	ds_read_b128 v[194:197], v3 offset:8896
	ds_read_b128 v[198:201], v3 offset:64
	s_waitcnt lgkmcnt(6)
	v_mfma_f32_16x16x32_bf16 v[78:81], v[74:77], v[78:81], 0
	v_add_u32_e32 v217, v2, v184
	v_add_u32_e32 v218, v3, v184
	s_lshl_b32 s16, s33, 5
	s_waitcnt lgkmcnt(4)
	v_mfma_f32_16x16x32_bf16 v[82:85], v[82:85], v[86:89], 0
	s_mov_b32 s93, 0x8000
	s_waitcnt lgkmcnt(2)
	v_mfma_f32_16x16x32_bf16 v[78:81], v[150:153], v[190:193], v[78:81]
	ds_read_b128 v[190:193], v2 offset:8960
	ds_read_b128 v[202:205], v2 offset:128
	s_waitcnt lgkmcnt(2)
	v_mfma_f32_16x16x32_bf16 v[82:85], v[194:197], v[198:201], v[82:85]
	ds_read_b128 v[194:197], v3 offset:8960
	ds_read_b128 v[208:211], v3 offset:128
	s_waitcnt lgkmcnt(2)
	v_mfma_f32_16x16x32_bf16 v[78:81], v[190:193], v[202:205], v[78:81]
	ds_read_b128 v[202:205], v3 offset:9024
	ds_read_b128 v[212:215], v3 offset:192
	s_waitcnt lgkmcnt(2)
	v_mfma_f32_16x16x32_bf16 v[82:85], v[194:197], v[208:211], v[82:85]
	ds_read_b128 v[194:197], v2 offset:9024
	s_waitcnt lgkmcnt(1)
	v_mfma_f32_16x16x32_bf16 v[82:85], v[202:205], v[212:215], v[82:85]
	ds_read_b128 v[202:205], v2 offset:192
	v_mfma_f32_16x16x32_bf16 v[74:77], v[74:77], v[86:89], 0
	v_cvt_pk_bf16_f32 v86, v62, v63
	s_nop 4
	v_cndmask_b32_e64 v4, v85, 0, s[10:11]
	v_cndmask_b32_e64 v154, v84, 0, s[12:13]
	s_waitcnt lgkmcnt(0)
	v_mfma_f32_16x16x32_bf16 v[78:81], v[194:197], v[202:205], v[78:81]
	v_cndmask_b32_e64 v155, v83, 0, s[0:1]
	v_cndmask_b32_e64 v216, v82, 0, s[86:87]
	ds_read2_b64 v[82:85], v218 offset1:4
	v_mfma_f32_16x16x32_bf16 v[74:77], v[150:153], v[198:201], v[74:77]
	v_cvt_pk_bf16_f32 v87, v64, v65
	s_nop 2
	v_cndmask_b32_e64 v202, v81, 0, s[10:11]
	v_cndmask_b32_e64 v203, v80, 0, s[12:13]
	v_cndmask_b32_e64 v204, v79, 0, s[0:1]
	v_cndmask_b32_e64 v198, v78, 0, s[86:87]
	ds_read2_b64 v[78:81], v217 offset1:4
	v_mfma_f32_16x16x32_bf16 v[74:77], v[190:193], v[208:211], v[74:77]
	v_cvt_pk_bf16_f32 v2, v198, v204
	ds_read2_b64 v[198:201], v218 offset0:8 offset1:12
	v_cvt_pk_bf16_f32 v88, v66, v67
	v_mfma_f32_16x16x32_bf16 v[74:77], v[194:197], v[212:215], v[74:77]
	ds_read2_b64 v[194:197], v217 offset0:8 offset1:12
	v_cvt_pk_bf16_f32 v89, v68, v69
	v_cvt_pk_bf16_f32 v190, v34, v35
	v_cvt_pk_bf16_f32 v191, v36, v37
	s_waitcnt lgkmcnt(2)
	v_mfma_f32_16x16x32_bf16 v[150:153], v[78:81], v[86:89], 0
	v_cvt_pk_bf16_f32 v192, v30, v31
	v_cvt_pk_bf16_f32 v193, v32, v33
	v_cvt_pk_bf16_f32 v3, v203, v202
	v_mfma_f32_16x16x32_bf16 v[86:89], v[82:85], v[86:89], 0
	v_cvt_pk_bf16_f32 v202, v54, v55
	v_cvt_pk_bf16_f32 v203, v56, v57
	v_cvt_pk_bf16_f32 v204, v58, v59
	v_mfma_f32_16x16x32_bf16 v[78:81], v[78:81], v[190:193], 0
	v_cvt_pk_bf16_f32 v205, v60, v61
	v_cvt_pk_bf16_f32 v208, v46, v47
	v_cvt_pk_bf16_f32 v209, v48, v49
	v_mfma_f32_16x16x32_bf16 v[82:85], v[82:85], v[190:193], 0
	v_cvt_pk_bf16_f32 v190, v26, v27
	v_cvt_pk_bf16_f32 v191, v28, v29
	v_cvt_pk_bf16_f32 v192, v22, v23
	s_waitcnt lgkmcnt(0)
	v_mfma_f32_16x16x32_bf16 v[150:153], v[194:197], v[202:205], v[150:153]
	v_cvt_pk_bf16_f32 v193, v24, v25
	v_cvt_pk_bf16_f32 v210, v50, v51
	v_cvt_pk_bf16_f32 v211, v52, v53
	v_mfma_f32_16x16x32_bf16 v[86:89], v[198:201], v[202:205], v[86:89]
	ds_read2_b64 v[202:205], v217 offset0:16 offset1:20
	v_cvt_pk_bf16_f32 v74, v74, v75
	v_cvt_pk_bf16_f32 v75, v76, v77
	v_mfma_f32_16x16x32_bf16 v[78:81], v[194:197], v[190:193], v[78:81]
	ds_read2_b64 v[194:197], v218 offset0:16 offset1:20
	v_cvt_pk_bf16_f32 v77, v154, v4
	v_add_u32_e32 v154, s92, v179
	v_mfma_f32_16x16x32_bf16 v[82:85], v[198:201], v[190:193], v[82:85]
	ds_read2_b64 v[198:201], v217 offset0:24 offset1:28
	v_cvt_pk_bf16_f32 v190, v18, v19
	v_cvt_pk_bf16_f32 v191, v20, v21
	v_cvt_pk_bf16_f32 v192, v14, v15
	v_cvt_pk_bf16_f32 v193, v16, v17
	s_waitcnt lgkmcnt(2)
	v_mfma_f32_16x16x32_bf16 v[150:153], v[202:205], v[208:211], v[150:153]
	v_mov_b32_e32 v4, v5
	v_cvt_pk_bf16_f32 v76, v216, v155
	v_mov_b32_e32 v155, v5
	v_mfma_f32_16x16x32_bf16 v[78:81], v[202:205], v[190:193], v[78:81]
	ds_read2_b64 v[202:205], v218 offset0:24 offset1:28
	s_waitcnt lgkmcnt(2)
	v_mfma_f32_16x16x32_bf16 v[86:89], v[194:197], v[208:211], v[86:89]
	v_cvt_pk_bf16_f32 v208, v38, v39
	v_cvt_pk_bf16_f32 v209, v40, v41
	v_cvt_pk_bf16_f32 v210, v42, v43
	v_mfma_f32_16x16x32_bf16 v[82:85], v[194:197], v[190:193], v[82:85]
	v_cvt_pk_bf16_f32 v211, v44, v45
	v_cvt_pk_bf16_f32 v190, v10, v11
	v_cvt_pk_bf16_f32 v191, v12, v13
	v_cvt_pk_bf16_f32 v192, v6, v7
	v_cvt_pk_bf16_f32 v193, v8, v9
	s_waitcnt lgkmcnt(1)
	v_mfma_f32_16x16x32_bf16 v[150:153], v[198:201], v[208:211], v[150:153]
	v_mfma_f32_16x16x32_bf16 v[78:81], v[198:201], v[190:193], v[78:81]
	v_lshlrev_b32_e32 v198, 1, v178
	v_add3_u32 v199, v154, v185, v198
	v_add_u32_e32 v154, 0x6800, v199
	ds_read2_b64 v[194:197], v154 offset0:160 offset1:164
	s_waitcnt lgkmcnt(1)
	v_mfma_f32_16x16x32_bf16 v[86:89], v[202:205], v[208:211], v[86:89]
	v_or_b32_e32 v154, s16, v178
	v_mfma_f32_16x16x32_bf16 v[82:85], v[202:205], v[190:193], v[82:85]
	s_waitcnt lgkmcnt(0)
; #define LAS __attribute__((address_space(3)))
; #define MFMA16(a, b, c) __builtin_amdgcn_mfma_f32_16x16x32_bf16((a), (b), (c), 0, 0, 0)
; __device__ __forceinline__ void hgrn_local_ws2(Frame& F, int item) {
;     ...
; #pragma unroll
;             for (int g = 0; g < 2; ++g) {
;                 const LAS bf16* vrow = VT + VTOFF(32 * w + 16 * g + l15);
;                 const bf16x8 bv = join8(*(const LAS v2u*)(vrow + 4 * quad), *(const LAS v2u*)(vrow + 16 + 4 * quad));
;                 O[g][0] = MFMA16(a0, bv, O[g][0]); O[g][1] = MFMA16(a1, bv, O[g][1]);
;                 float* op = F.OLOC + (row0 + (size_t)(ch * 32 + 4 * quad)) * 512 + h * 128 + 32 * w + 16 * g + l15;
; #pragma unroll
;                 for (int r = 0; r < 4; ++r) { op[(size_t)r * 512] = O[g][0][r]; op[(size_t)(16 + r) * 512] = O[g][1][r]; }
;             }
;             const bf16x8 bvn0 = *(const LAS bf16x8*)(VT + VTOFF(32 * w + l15) + 8 * quad), bvn1 = *(const LAS bf16x8*)(VT + VTOFF(32 * w + 16 + l15) + 8 * quad);
; #pragma unroll
;             for (int tc = 0; tc < 8; ++tc) {
;                 const f32x4 dec = *(const LAS f32x4*)(DEC + 16 * tc + 4 * quad);
;                 const bf16x8 ak = *(const LAS bf16x8*)(KDT + (16 * tc + l15) * KT_STRIDE + 8 * quad);
;                 S[0][tc] = S[0][tc] * dec; S[1][tc] = S[1][tc] * dec;
;                 S[0][tc] = MFMA16(ak, bvn0, S[0][tc]); S[1][tc] = MFMA16(ak, bvn1, S[1][tc]);
;             }
	v_mfma_f32_16x16x32_bf16 v[190:193], v[2:5], v[194:197], v[150:153]
	s_nop 2
	v_lshl_add_u64 v[150:151], s[88:89], 0, v[154:155]
	v_lshlrev_b64 v[150:151], 11, v[150:151]
	v_lshl_add_u64 v[208:209], v[148:149], 0, v[150:151]
	v_mfma_f32_16x16x32_bf16 v[86:89], v[74:77], v[194:197], v[86:89]
	v_add_co_u32_e32 v154, vcc, s93, v208
	s_mov_b32 s93, 0x9000
	s_nop 0
	v_addc_co_u32_e32 v155, vcc, 0, v209, vcc
	v_add_co_u32_e32 v150, vcc, s93, v208
	global_store_dword v[208:209], v190, off
	s_nop 0
	v_addc_co_u32_e32 v151, vcc, 0, v209, vcc
	global_store_dword v[150:151], v86, off offset:-4096
	global_store_dword v[208:209], v191, off offset:2048
	global_store_dword v[154:155], v87, off offset:2048
	v_add_u32_e32 v86, s92, v180
	v_add3_u32 v198, v86, v186, v198
	v_add_u32_e32 v86, 0x6800, v198
	ds_read2_b64 v[194:197], v86 offset0:160 offset1:164
	v_add_co_u32_e32 v152, vcc, s67, v208
	s_waitcnt lgkmcnt(0)
	v_mfma_f32_16x16x32_bf16 v[78:81], v[2:5], v[194:197], v[78:81]
	v_addc_co_u32_e32 v153, vcc, 0, v209, vcc
	global_store_dword v[152:153], v192, off
	global_store_dword v[150:151], v88, off
	global_store_dword v[152:153], v193, off offset:2048
	global_store_dword v[150:151], v89, off offset:2048
	v_add_u32_e32 v3, v207, v182
	v_add_u32_e32 v4, v199, v176
	v_mfma_f32_16x16x32_bf16 v[74:77], v[74:77], v[194:197], v[82:85]
	v_add_u32_e32 v2, s92, v181
	ds_read_b128 v[190:193], v3 offset:17664
	ds_read_b128 v[194:197], v2 offset:39104
	ds_read_b128 v[86:89], v4 offset:27904
	v_add_u32_e32 v4, v198, v176
	ds_read_b128 v[198:201], v3 offset:18944
	ds_read_b128 v[202:205], v2 offset:39168
	ds_read_b128 v[82:85], v4 offset:27904
	ds_read_b128 v[240:243], v3 offset:20224
	ds_read_b128 v[248:251], v2 offset:39232
	ds_read_b128 v[244:247], v3 offset:21504
	ds_read_b128 v[252:255], v2 offset:39296
	s_waitcnt lgkmcnt(4)
	v_pk_mul_f32 v[64:65], v[64:65], v[196:197]
	v_pk_mul_f32 v[62:63], v[62:63], v[194:195]
	v_pk_mul_f32 v[36:37], v[36:37], v[196:197]
	v_pk_mul_f32 v[34:35], v[34:35], v[194:195]
	global_store_dword v[208:209], v78, off offset:64
	s_andn2_b64 vcc, exec, s[90:91]
	s_mov_b32 s92, 8
	v_mfma_f32_16x16x32_bf16 v[62:65], v[190:193], v[86:89], v[62:65]
	v_mfma_f32_16x16x32_bf16 v[34:37], v[190:193], v[82:85], v[34:37]
	ds_read_b128 v[190:193], v3 offset:22784
	ds_read_b128 v[194:197], v2 offset:39360
	v_pk_mul_f32 v[68:69], v[68:69], v[204:205]
	v_pk_mul_f32 v[66:67], v[66:67], v[202:203]
	v_pk_mul_f32 v[32:33], v[32:33], v[204:205]
	v_pk_mul_f32 v[30:31], v[30:31], v[202:203]
	global_store_dword v[154:155], v74, off offset:64
	global_store_dword v[208:209], v79, off offset:2112
	v_mfma_f32_16x16x32_bf16 v[66:69], v[198:201], v[86:89], v[66:69]
	v_mfma_f32_16x16x32_bf16 v[30:33], v[198:201], v[82:85], v[30:33]
	ds_read_b128 v[198:201], v3 offset:24064
	ds_read_b128 v[202:205], v2 offset:39424
	s_waitcnt lgkmcnt(6)
	v_pk_mul_f32 v[56:57], v[56:57], v[250:251]
	v_pk_mul_f32 v[54:55], v[54:55], v[248:249]
	v_pk_mul_f32 v[28:29], v[28:29], v[250:251]
	v_pk_mul_f32 v[26:27], v[26:27], v[248:249]
	s_nop 1
	v_mfma_f32_16x16x32_bf16 v[54:57], v[240:243], v[86:89], v[54:57]
	v_mfma_f32_16x16x32_bf16 v[26:29], v[240:243], v[82:85], v[26:29]
	ds_read_b128 v[240:243], v3 offset:25344
	ds_read_b128 v[248:251], v2 offset:39488
	s_waitcnt lgkmcnt(6)
	v_pk_mul_f32 v[60:61], v[60:61], v[254:255]
	v_pk_mul_f32 v[58:59], v[58:59], v[252:253]
	v_pk_mul_f32 v[24:25], v[24:25], v[254:255]
	v_pk_mul_f32 v[22:23], v[22:23], v[252:253]
	global_store_dword v[154:155], v75, off offset:2112
	global_store_dword v[152:153], v80, off offset:64
	v_mfma_f32_16x16x32_bf16 v[58:61], v[244:247], v[86:89], v[58:61]
	v_mfma_f32_16x16x32_bf16 v[22:25], v[244:247], v[82:85], v[22:25]
	ds_read_b128 v[244:247], v3 offset:26624
	ds_read_b128 v[252:255], v2 offset:39552
	s_waitcnt lgkmcnt(6)
	v_pk_mul_f32 v[48:49], v[48:49], v[196:197]
	v_pk_mul_f32 v[46:47], v[46:47], v[194:195]
	v_pk_mul_f32 v[20:21], v[20:21], v[196:197]
	v_pk_mul_f32 v[18:19], v[18:19], v[194:195]
	s_nop 1
	v_mfma_f32_16x16x32_bf16 v[46:49], v[190:193], v[86:89], v[46:49]
	v_mfma_f32_16x16x32_bf16 v[18:21], v[190:193], v[82:85], v[18:21]
	s_waitcnt lgkmcnt(4)
	v_pk_mul_f32 v[52:53], v[52:53], v[204:205]
	v_pk_mul_f32 v[50:51], v[50:51], v[202:203]
	v_pk_mul_f32 v[16:17], v[16:17], v[204:205]
	v_pk_mul_f32 v[14:15], v[14:15], v[202:203]
	global_store_dword v[150:151], v76, off offset:64
	global_store_dword v[152:153], v81, off offset:2112
	v_mfma_f32_16x16x32_bf16 v[50:53], v[198:201], v[86:89], v[50:53]
	v_mfma_f32_16x16x32_bf16 v[14:17], v[198:201], v[82:85], v[14:17]
	s_waitcnt lgkmcnt(2)
	v_pk_mul_f32 v[40:41], v[40:41], v[250:251]
	v_pk_mul_f32 v[38:39], v[38:39], v[248:249]
	v_pk_mul_f32 v[12:13], v[12:13], v[250:251]
	v_pk_mul_f32 v[10:11], v[10:11], v[248:249]
	global_store_dword v[150:151], v77, off offset:2112
	s_nop 1
	v_mfma_f32_16x16x32_bf16 v[38:41], v[240:243], v[86:89], v[38:41]
	v_mfma_f32_16x16x32_bf16 v[10:13], v[240:243], v[82:85], v[10:13]
	s_waitcnt lgkmcnt(0)
	v_pk_mul_f32 v[44:45], v[44:45], v[254:255]
	v_pk_mul_f32 v[42:43], v[42:43], v[252:253]
	v_pk_mul_f32 v[8:9], v[8:9], v[254:255]
	v_pk_mul_f32 v[6:7], v[6:7], v[252:253]
	s_nop 1
	v_mfma_f32_16x16x32_bf16 v[42:45], v[244:247], v[86:89], v[42:45]
	v_mfma_f32_16x16x32_bf16 v[6:9], v[244:247], v[82:85], v[6:9]
	s_cbranch_vccnz .LBB0_474
	s_waitcnt vmcnt(31)
	v_lshlrev_b32_e32 v2, 16, v119
	v_add_f32_e32 v4, 0, v2
	s_waitcnt vmcnt(29)
	v_lshlrev_b32_e32 v2, 16, v123
	v_add_f32_e32 v80, v4, v2
	s_waitcnt vmcnt(27)
	v_lshlrev_b32_e32 v2, 16, v127
	v_add_f32_e32 v82, v80, v2
	s_waitcnt vmcnt(25)
	v_lshlrev_b32_e32 v2, 16, v131
	v_add_f32_e32 v84, v82, v2
	s_waitcnt vmcnt(23)
	v_lshlrev_b32_e32 v2, 16, v135
	v_add_f32_e32 v86, v84, v2
	s_waitcnt vmcnt(21)
	v_lshlrev_b32_e32 v2, 16, v139
	v_add_f32_e32 v88, v86, v2
	s_waitcnt vmcnt(19)
	v_lshlrev_b32_e32 v2, 16, v187
	v_add_f32_e32 v150, v88, v2
	s_waitcnt vmcnt(17)
	v_lshlrev_b32_e32 v2, 16, v189
	v_add_f32_e32 v152, v150, v2
	ds_bpermute_b32 v2, v91, v152
	ds_bpermute_b32 v74, v93, v152
	ds_bpermute_b32 v3, v95, v152
	ds_bpermute_b32 v75, v97, v152
	s_add_i32 s92, s33, 1
	s_waitcnt lgkmcnt(3)
	v_cndmask_b32_e64 v76, v2, 0, s[4:5]
	s_waitcnt lgkmcnt(2)
	v_cndmask_b32_e64 v77, 0, v74, s[6:7]
	v_add_f32_e32 v76, v76, v77
	s_waitcnt lgkmcnt(1)
	v_cndmask_b32_e64 v77, 0, v3, s[8:9]
	v_add_f32_e32 v153, v76, v77
	s_waitcnt lgkmcnt(0)
	v_pk_add_f32 v[2:3], v[2:3], v[74:75]
	v_mul_f32_e32 v74, 0x3fb8aa3b, v153
	v_add_f32_e32 v4, v4, v153
	v_exp_f32_e32 v74, v74
	v_mul_f32_e32 v4, 0x3fb8aa3b, v4
	v_exp_f32_e32 v76, v4
	v_add_f32_e32 v3, v2, v3
	v_rcp_f32_e32 v74, v74
	v_mul_f32_e32 v2, 0x3fb8aa3b, v115
	v_rcp_f32_e32 v77, v76
	s_bitcmp1_b32 s92, 0
	v_exp_f32_e32 v154, v2
	s_cselect_b32 s90, 0x9ac0, 0
	v_fma_f32 v75, -v74, v76, 1.0
	v_lshlrev_b32_e32 v74, 16, v117
	s_add_i32 s93, s90, 0
	v_pk_mul_f32 v[74:75], v[76:77], v[74:75]
	v_lshl_add_u32 v76, v99, 1, s93
	v_cvt_pk_bf16_f32 v4, v74, v75
	ds_write_b16 v76, v4
	ds_write_b16_d16_hi v76, v4 offset:8832
	v_mul_f32_e32 v4, v154, v74
	s_lshl_b32 s90, s92, 5
	v_bfe_u32 v74, v4, 16, 1
	v_add3_u32 v74, v4, v74, s96
	v_or_b32_e32 v4, s90, v90
	v_lshl_add_u64 v[78:79], s[88:89], 0, v[4:5]
	v_lshlrev_b64 v[78:79], 10, v[78:79]
	v_add_f32_e32 v4, v80, v153
	v_lshl_add_u64 v[78:79], v[146:147], 0, v[78:79]
	v_mul_f32_e32 v4, 0x3fb8aa3b, v4
	global_store_short_d16_hi v[78:79], v74, off
	v_exp_f32_e32 v78, v4
	v_lshlrev_b32_e32 v76, 16, v121
	v_lshl_add_u32 v74, v103, 1, s93
	v_mul_f32_e32 v2, 0x3fb8aa3b, v3
	v_rcp_f32_e32 v79, v78
	v_fma_f32 v77, -v78, v77, 1.0
	v_exp_f32_e32 v2, v2
	v_pk_mul_f32 v[76:77], v[78:79], v[76:77]
	s_nop 0
	v_cvt_pk_bf16_f32 v4, v76, v77
	ds_write_b16 v74, v4
	ds_write_b16_d16_hi v74, v4 offset:8832
	v_mul_f32_e32 v4, v154, v76
	v_bfe_u32 v74, v4, 16, 1
	v_add3_u32 v74, v4, v74, s96
	v_or_b32_e32 v4, s90, v92
	v_lshl_add_u64 v[80:81], s[88:89], 0, v[4:5]
	v_lshlrev_b64 v[80:81], 10, v[80:81]
	v_add_f32_e32 v4, v82, v153
	v_lshl_add_u64 v[80:81], v[146:147], 0, v[80:81]
	v_mul_f32_e32 v4, 0x3fb8aa3b, v4
	global_store_short_d16_hi v[80:81], v74, off
	v_exp_f32_e32 v80, v4
	v_lshlrev_b32_e32 v78, 16, v125
	v_lshl_add_u32 v74, v156, 1, s93
	v_rcp_f32_e32 v81, v80
	v_fma_f32 v79, -v80, v79, 1.0
	v_pk_mul_f32 v[78:79], v[80:81], v[78:79]
	s_nop 0
	v_cvt_pk_bf16_f32 v4, v78, v79
	ds_write_b16 v74, v4
	ds_write_b16_d16_hi v74, v4 offset:8832
	v_mul_f32_e32 v4, v154, v78
	v_bfe_u32 v74, v4, 16, 1
	v_add3_u32 v74, v4, v74, s96
	v_or_b32_e32 v4, s90, v94
	v_lshl_add_u64 v[82:83], s[88:89], 0, v[4:5]
	v_lshlrev_b64 v[82:83], 10, v[82:83]
	v_add_f32_e32 v4, v84, v153
	v_lshl_add_u64 v[82:83], v[146:147], 0, v[82:83]
	v_mul_f32_e32 v4, 0x3fb8aa3b, v4
	global_store_short_d16_hi v[82:83], v74, off
	v_exp_f32_e32 v82, v4
	v_lshlrev_b32_e32 v80, 16, v129
	v_lshl_add_u32 v74, v158, 1, s93
	v_mov_b32_e32 v78, v75
	v_rcp_f32_e32 v83, v82
	v_fma_f32 v81, -v82, v81, 1.0
	v_pk_mul_f32 v[80:81], v[82:83], v[80:81]
	s_nop 0
	v_cvt_pk_bf16_f32 v4, v80, v81
	ds_write_b16 v74, v4
	ds_write_b16_d16_hi v74, v4 offset:8832
	v_mul_f32_e32 v4, v154, v80
	v_bfe_u32 v74, v4, 16, 1
	v_add3_u32 v74, v4, v74, s96
	v_or_b32_e32 v4, s90, v96
	v_lshl_add_u64 v[84:85], s[88:89], 0, v[4:5]
	v_lshlrev_b64 v[84:85], 10, v[84:85]
	v_add_f32_e32 v4, v86, v153
	v_lshl_add_u64 v[84:85], v[146:147], 0, v[84:85]
	v_mul_f32_e32 v4, 0x3fb8aa3b, v4
	global_store_short_d16_hi v[84:85], v74, off
	v_exp_f32_e32 v84, v4
	v_lshlrev_b32_e32 v82, 16, v133
	v_lshl_add_u32 v74, v160, 1, s93
	v_mov_b32_e32 v80, v77
	v_rcp_f32_e32 v85, v84
	v_fma_f32 v83, -v84, v83, 1.0
	v_pk_mul_f32 v[76:77], v[2:3], v[80:81] op_sel_hi:[0,1]
	v_pk_mul_f32 v[82:83], v[84:85], v[82:83]
	s_nop 0
	v_cvt_pk_bf16_f32 v4, v82, v83
	ds_write_b16 v74, v4
	ds_write_b16_d16_hi v74, v4 offset:8832
	v_mul_f32_e32 v4, v154, v82
	v_bfe_u32 v74, v4, 16, 1
	v_add3_u32 v74, v4, v74, s96
	v_or_b32_e32 v4, s90, v98
	v_lshl_add_u64 v[86:87], s[88:89], 0, v[4:5]
	v_lshlrev_b64 v[86:87], 10, v[86:87]
	v_add_f32_e32 v4, v88, v153
	v_lshl_add_u64 v[86:87], v[146:147], 0, v[86:87]
	v_mul_f32_e32 v4, 0x3fb8aa3b, v4
	global_store_short_d16_hi v[86:87], v74, off
	v_exp_f32_e32 v86, v4
	v_lshlrev_b32_e32 v84, 16, v137
	v_lshl_add_u32 v74, v162, 1, s93
	v_rcp_f32_e32 v87, v86
	v_fma_f32 v85, -v86, v85, 1.0
	v_pk_mul_f32 v[84:85], v[86:87], v[84:85]
	s_nop 0
	v_cvt_pk_bf16_f32 v4, v84, v85
	ds_write_b16 v74, v4
	ds_write_b16_d16_hi v74, v4 offset:8832
	v_mul_f32_e32 v4, v154, v84
	v_bfe_u32 v74, v4, 16, 1
	v_add3_u32 v74, v4, v74, s96
	v_or_b32_e32 v4, s90, v100
	v_lshl_add_u64 v[88:89], s[88:89], 0, v[4:5]
	v_lshlrev_b64 v[88:89], 10, v[88:89]
	v_add_f32_e32 v4, v150, v153
	v_lshl_add_u64 v[88:89], v[146:147], 0, v[88:89]
	v_mul_f32_e32 v4, 0x3fb8aa3b, v4
	global_store_short_d16_hi v[88:89], v74, off
	v_exp_f32_e32 v88, v4
	v_lshlrev_b32_e32 v86, 16, v141
	v_lshl_add_u32 v74, v164, 1, s93
	v_bfe_u32 v84, v76, 16, 1
	v_rcp_f32_e32 v89, v88
	v_fma_f32 v87, -v88, v87, 1.0
	v_add3_u32 v84, v76, v84, s96
	v_pk_mul_f32 v[86:87], v[88:89], v[86:87]
	s_nop 0
	v_cvt_pk_bf16_f32 v4, v86, v87
	ds_write_b16 v74, v4
	ds_write_b16_d16_hi v74, v4 offset:8832
	v_mul_f32_e32 v4, v154, v86
	v_bfe_u32 v74, v4, 16, 1
	v_add3_u32 v74, v4, v74, s96
	v_or_b32_e32 v4, s90, v102
	v_lshl_add_u64 v[150:151], s[88:89], 0, v[4:5]
	v_lshlrev_b64 v[150:151], 10, v[150:151]
	v_add_f32_e32 v4, v152, v153
	v_lshl_add_u64 v[150:151], v[146:147], 0, v[150:151]
	v_mul_f32_e32 v4, 0x3fb8aa3b, v4
	global_store_short_d16_hi v[150:151], v74, off
	v_exp_f32_e32 v150, v4
	v_lshlrev_b32_e32 v88, 16, v188
	v_lshl_add_u32 v74, v166, 1, s93
	v_mov_b32_e32 v86, v83
	v_rcp_f32_e32 v151, v150
	v_fma_f32 v89, -v150, v89, 1.0
	v_bfe_u32 v83, v77, 16, 1
	v_add3_u32 v83, v77, v83, s96
	v_pk_mul_f32 v[88:89], v[150:151], v[88:89]
	s_nop 0
	v_cvt_pk_bf16_f32 v4, v88, v89
	ds_write_b16 v74, v4
	ds_write_b16_d16_hi v74, v4 offset:8832
	v_mul_f32_e32 v4, v154, v88
	v_bfe_u32 v74, v4, 16, 1
	v_add3_u32 v74, v4, v74, s96
	v_or_b32_e32 v4, s90, v104
	v_lshl_add_u64 v[150:151], s[88:89], 0, v[4:5]
	v_lshlrev_b64 v[150:151], 10, v[150:151]
	v_mov_b32_e32 v88, v85
	v_lshl_add_u64 v[150:151], v[146:147], 0, v[150:151]
	v_pk_mul_f32 v[80:81], v[2:3], v[88:89] op_sel_hi:[0,1]
	global_store_short_d16_hi v[150:151], v74, off
	v_pk_mul_f32 v[74:75], v[2:3], v[78:79] op_sel_hi:[0,1]
	v_pk_mul_f32 v[78:79], v[2:3], v[86:87] op_sel_hi:[0,1]
	v_bfe_u32 v82, v80, 16, 1
	v_bfe_u32 v4, v81, 16, 1
	v_add3_u32 v76, v80, v82, s96
	v_bfe_u32 v82, v79, 16, 1
	v_add3_u32 v4, v81, v4, s96
	v_bfe_u32 v77, v74, 16, 1
	v_bfe_u32 v80, v75, 16, 1
	v_bfe_u32 v81, v78, 16, 1
	v_add3_u32 v79, v79, v82, s96
	v_add3_u32 v78, v78, v81, s96
	v_add3_u32 v75, v75, v80, s96
	v_add3_u32 v74, v74, v77, s96
	v_lshrrev_b32_e32 v77, 16, v79
	v_lshrrev_b32_e32 v74, 16, v74
	v_lshrrev_b32_e32 v75, 16, v75
	v_lshrrev_b32_e32 v78, 16, v78
	v_and_or_b32 v77, v4, s97, v77
	v_lshl_add_u32 v4, v168, 1, s93
	v_and_or_b32 v76, v76, s97, v78
	v_and_or_b32 v75, v83, s97, v75
	v_and_or_b32 v74, v84, s97, v74
	v_lshl_add_u32 v78, v90, 1, v4
	ds_write_b128 v78, v[74:77] offset:17664
	s_and_saveexec_b64 s[90:91], s[4:5]
	v_add_u32_e32 v4, v4, v183
	ds_write_b32 v4, v2 offset:39104
	s_or_b64 exec, exec, s[90:91]
	v_add_u32_e32 v2, s93, v170
	v_add3_u32 v2, v2, v171, v172
	s_cmp_gt_u32 s33, 5
	s_waitcnt vmcnt(24)
	ds_write_b16 v2, v70 offset:27904
	ds_write_b16_d16_hi v2, v70 offset:27984
	ds_write_b16 v2, v71 offset:28064
	ds_write_b16_d16_hi v2, v71 offset:28144
	ds_write_b16 v2, v72 offset:28224
	ds_write_b16_d16_hi v2, v72 offset:28304
	ds_write_b16 v2, v73 offset:28384
	ds_write_b16_d16_hi v2, v73 offset:28464
	s_cbranch_scc1 .LBB0_473
	s_add_i32 s16, s16, 64
	v_or_b32_e32 v2, s16, v90
	v_mul_lo_u32 v4, v2, s63
	v_lshl_add_u64 v[70:71], v[4:5], 1, v[142:143]
	v_add_co_u32_e32 v72, vcc, 0x1000, v70
	global_load_ushort v117, v[70:71], off
	global_load_ushort v119, v[70:71], off offset:1024
	v_addc_co_u32_e32 v73, vcc, 0, v71, vcc
	global_load_ushort v121, v[72:73], off offset:1536
	global_load_ushort v123, v[72:73], off offset:2560
	v_add_co_u32_e32 v72, vcc, 0x2000, v70
	v_or_b32_e32 v2, s16, v1
	s_nop 0
	v_addc_co_u32_e32 v73, vcc, 0, v71, vcc
	global_load_ushort v125, v[72:73], off offset:3072
	v_add_co_u32_e32 v72, vcc, 0x3000, v70
	v_mul_lo_u32 v4, v2, s63
	s_nop 0
	v_addc_co_u32_e32 v73, vcc, 0, v71, vcc
	global_load_ushort v127, v[72:73], off
	v_add_co_u32_e32 v72, vcc, 0x4000, v70
	s_nop 1
	v_addc_co_u32_e32 v73, vcc, 0, v71, vcc
	global_load_ushort v129, v[72:73], off offset:512
	global_load_ushort v131, v[72:73], off offset:1536
	v_add_co_u32_e32 v72, vcc, 0x5000, v70
	s_nop 1
	v_addc_co_u32_e32 v73, vcc, 0, v71, vcc
	global_load_ushort v133, v[72:73], off offset:2048
	global_load_ushort v135, v[72:73], off offset:3072
	v_add_co_u32_e32 v72, vcc, 0x6000, v70
	s_nop 1
	v_addc_co_u32_e32 v73, vcc, 0, v71, vcc
	global_load_ushort v137, v[72:73], off offset:3584
	v_add_co_u32_e32 v72, vcc, 0x7000, v70
	s_nop 1
	v_addc_co_u32_e32 v73, vcc, 0, v71, vcc
	global_load_ushort v139, v[72:73], off offset:512
	v_add_co_u32_e32 v72, vcc, 0x8000, v70
	s_nop 1
	v_addc_co_u32_e32 v73, vcc, 0, v71, vcc
	v_add_co_u32_e32 v70, vcc, 0x9000, v70
	global_load_ushort v141, v[72:73], off offset:1024
	global_load_ushort v187, v[72:73], off offset:2048
	v_addc_co_u32_e32 v71, vcc, 0, v71, vcc
	global_load_ushort v188, v[70:71], off offset:2560
	global_load_ushort v189, v[70:71], off offset:3584
	v_lshl_add_u64 v[70:71], v[4:5], 1, v[144:145]
	global_load_dwordx4 v[70:73], v[70:71], off offset:2048

; template <bool COOP>
; __global__ void __launch_bounds__(NWAVES * 64, 2) fwd(Args args) {
	.amdhsa_kernel _Z3fwdILb1EEv4Args
		.amdhsa_group_segment_fixed_size 0
		.amdhsa_private_segment_fixed_size 0
		.amdhsa_kernarg_size 384
		.amdhsa_user_sgpr_count 2
		.amdhsa_user_sgpr_dispatch_ptr 0
		.amdhsa_user_sgpr_queue_ptr 0
		.amdhsa_user_sgpr_kernarg_segment_ptr 1
		.amdhsa_user_sgpr_dispatch_id 0
		.amdhsa_user_sgpr_kernarg_preload_length 0
		.amdhsa_user_sgpr_kernarg_preload_offset 0
		.amdhsa_user_sgpr_private_segment_size 0
		.amdhsa_uses_dynamic_stack 0
		.amdhsa_enable_private_segment 0
		.amdhsa_system_sgpr_workgroup_id_x 1
		.amdhsa_system_sgpr_workgroup_id_y 0
		.amdhsa_system_sgpr_workgroup_id_z 0
		.amdhsa_system_sgpr_workgroup_info 0
		.amdhsa_system_vgpr_workitem_id 0
		.amdhsa_next_free_vgpr 256
		.amdhsa_next_free_sgpr 102
		.amdhsa_accum_offset 256
		.amdhsa_reserve_vcc 1
		.amdhsa_float_round_mode_32 0
		.amdhsa_float_round_mode_16_64 0
		.amdhsa_float_denorm_mode_32 3
		.amdhsa_float_denorm_mode_16_64 3
		.amdhsa_dx10_clamp 1
		.amdhsa_ieee_mode 1
		.amdhsa_fp16_overflow 0
		.amdhsa_tg_split 0
		.amdhsa_exception_fp_ieee_invalid_op 0
		.amdhsa_exception_fp_denorm_src 0
		.amdhsa_exception_fp_ieee_div_zero 0
		.amdhsa_exception_fp_ieee_overflow 0
		.amdhsa_exception_fp_ieee_underflow 0
		.amdhsa_exception_fp_ieee_inexact 0
		.amdhsa_exception_int_div_zero 0
	.end_amdhsa_kernel

; template <bool COOP>
; __global__ void __launch_bounds__(NWAVES * 64, 2) fwd(Args args) {
amdhsa.kernels:
  - .agpr_count:     0
    .args:
      - .offset:         0
        .size:           128
        .value_kind:     by_value
      - .offset:         128
        .size:           4
        .value_kind:     hidden_block_count_x
      - .offset:         132
        .size:           4
        .value_kind:     hidden_block_count_y
      - .offset:         136
        .size:           4
        .value_kind:     hidden_block_count_z
      - .offset:         140
        .size:           2
        .value_kind:     hidden_group_size_x
      - .offset:         142
        .size:           2
        .value_kind:     hidden_group_size_y
      - .offset:         144
        .size:           2
        .value_kind:     hidden_group_size_z
      - .offset:         146
        .size:           2
        .value_kind:     hidden_remainder_x
      - .offset:         148
        .size:           2
        .value_kind:     hidden_remainder_y
      - .offset:         150
        .size:           2
        .value_kind:     hidden_remainder_z
      - .offset:         168
        .size:           8
        .value_kind:     hidden_global_offset_x
      - .offset:         176
        .size:           8
        .value_kind:     hidden_global_offset_y
      - .offset:         184
        .size:           8
        .value_kind:     hidden_global_offset_z
      - .offset:         192
        .size:           2
        .value_kind:     hidden_grid_dims
      - .offset:         248
        .size:           4
        .value_kind:     hidden_dynamic_lds_size
    .group_segment_fixed_size: 0
    .kernarg_segment_align: 8
    .kernarg_segment_size: 384
    .language:       OpenCL C
    .language_version:
      - 2
      - 0
    .max_flat_workgroup_size: 512
    .name:           _Z3fwdILb1EEv4Args
    .private_segment_fixed_size: 0
    .sgpr_count:     108
    .sgpr_spill_count: 16
    .symbol:         _Z3fwdILb1EEv4Args.kd
    .uniform_work_group_size: 1
    .uses_dynamic_stack: false
    .vgpr_count:     256
    .vgpr_spill_count: 0
    .wavefront_size: 64
  - .agpr_count:     0
    .args:
      - .offset:         0
        .size:           128
        .value_kind:     by_value
      - .offset:         128
        .size:           4
        .value_kind:     hidden_block_count_x
      - .offset:         132
        .size:           4
        .value_kind:     hidden_block_count_y
      - .offset:         136
        .size:           4
        .value_kind:     hidden_block_count_z
      - .offset:         140
        .size:           2
        .value_kind:     hidden_group_size_x
      - .offset:         142
        .size:           2
        .value_kind:     hidden_group_size_y
      - .offset:         144
        .size:           2
        .value_kind:     hidden_group_size_z
      - .offset:         146
        .size:           2
        .value_kind:     hidden_remainder_x
      - .offset:         148
        .size:           2
        .value_kind:     hidden_remainder_y
      - .offset:         150
        .size:           2
        .value_kind:     hidden_remainder_z
      - .offset:         168
        .size:           8
        .value_kind:     hidden_global_offset_x
      - .offset:         176
        .size:           8
        .value_kind:     hidden_global_offset_y
      - .offset:         184
        .size:           8
        .value_kind:     hidden_global_offset_z
      - .offset:         192
        .size:           2
        .value_kind:     hidden_grid_dims
      - .offset:         248
        .size:           4
        .value_kind:     hidden_dynamic_lds_size
    .group_segment_fixed_size: 0
    .kernarg_segment_align: 8
    .kernarg_segment_size: 384
    .language:       OpenCL C
    .language_version:
      - 2
      - 0
    .max_flat_workgroup_size: 512
    .name:           _Z3fwdILb0EEv4Args
    .private_segment_fixed_size: 0
    .sgpr_count:     104
    .sgpr_spill_count: 0
    .symbol:         _Z3fwdILb0EEv4Args.kd
    .uniform_work_group_size: 1
    .uses_dynamic_stack: false
    .vgpr_count:     238
    .vgpr_spill_count: 0
    .wavefront_size: 64
